# static s_setprio 1 for waves 4-7 inside the HGRN pass-2 chunk loop and the dilated-attention item loop (reset at their exits)
# baseline (speedup 1.0000x reference)
.LBB0_260:
	s_setprio 0
	v_readlane_b32 s50, v255, 28
	s_add_i32 s3, s3, s94
	s_add_i32 s2, s2, s94
	v_readlane_b32 s70, v255, 26
	v_readlane_b32 s51, v255, 29
	v_readlane_b32 s48, v255, 30
	v_readlane_b32 s74, v255, 32
	s_cmpk_gt_i32 s3, 0xff
	v_readlane_b32 s71, v255, 27
	v_readlane_b32 s49, v255, 31
	v_readlane_b32 s75, v255, 33
	v_readlane_b32 s51, v255, 34
	s_movk_i32 s78, 0xf800
	s_cbranch_scc1 .LBB0_374

.LBB0_268:
	s_lshl_b32 s18, s18, 10
	s_and_b32 s10, s10, 1
	s_ashr_i32 s0, s3, 7
	s_xor_b32 s19, s18, 0x1f80
	s_ashr_i32 s1, s0, 31
	s_lshl_b32 s4, s10, 25
	v_readlane_b32 s5, v250, 42
	s_add_u32 s20, s5, s4
	v_readlane_b32 s4, v250, 43
	s_addc_u32 s24, s4, 0
	s_lshl_b64 s[4:5], s[0:1], 24
	s_add_u32 s20, s20, s4
	s_addc_u32 s33, s24, s5
	v_readlane_b32 s0, v250, 44
	s_add_u32 s0, s0, s4
	v_readlane_b32 s1, v250, 45
	s_addc_u32 s1, s1, s5
	s_lshl_b32 s24, s3, 4
	s_and_b32 s36, s24, 0x700
	s_add_u32 s29, s0, s36
	s_addc_u32 s24, s1, 0
	s_cmp_eq_u32 s10, 0
	s_cselect_b64 s[48:49], -1, 0
	s_and_b64 s[0:1], s[48:49], exec
	s_cselect_b32 s1, s8, s76
	s_cselect_b32 s0, s9, s28
	s_add_u32 s37, s1, s4
	s_addc_u32 s50, s0, s5
	s_lshl_b32 s0, s54, 4
	s_ashr_i32 s1, s0, 31
	s_add_u32 s51, s80, s4
	s_addc_u32 s52, s81, s5
	s_add_u32 s25, s20, s36
	s_addc_u32 s10, s33, 0
	s_and_b64 s[4:5], s[48:49], exec
	s_cselect_b32 s56, 0x800, s78
	s_add_u32 s20, s37, s36
	s_addc_u32 s33, s50, 0
	s_lshl_b64 s[4:5], s[0:1], 1
	s_add_u32 s4, s20, s4
	s_addc_u32 s5, s33, s5
	s_add_u32 s33, s51, s36
	s_addc_u32 s20, s52, 0
	s_lshl_b32 s1, s21, 10
	v_cndmask_b32_e64 v32, v105, v99, s[48:49]
	s_xor_b32 s21, s1, 0x1fc0
	s_waitcnt vmcnt(0)
	v_lshl_or_b32 v66, v32, 11, v152
	s_and_b64 s[36:37], s[48:49], exec
	s_cselect_b32 s1, s1, s21
	v_add_u32_e32 v68, s56, v66
	s_lshl_b32 s1, s1, 11
	s_waitcnt vmcnt(38)
	v_add_u32_e32 v70, s56, v68
	s_add_u32 s36, s33, s1
	v_add_u32_e32 v72, s56, v70
	s_addc_u32 s37, s20, 0
	s_waitcnt vmcnt(29)
	v_add_u32_e32 v74, s56, v72
	s_add_u32 s50, s25, s1
	v_add_u32_e32 v76, s56, v74
	s_addc_u32 s51, s10, 0
	s_waitcnt vmcnt(28)
	v_add_u32_e32 v78, s56, v76
	s_add_u32 s52, s29, s1
	v_add_u32_e32 v80, s56, v78
	s_addc_u32 s53, s24, 0
	s_waitcnt vmcnt(19)
	v_add_u32_e32 v82, s56, v80
	v_add_u32_e32 v84, s56, v82
	s_waitcnt vmcnt(26)
	v_add_u32_e32 v86, s56, v84
	v_add_u32_e32 v88, s56, v86
	s_waitcnt vmcnt(20)
	v_add_u32_e32 v90, s56, v88
	v_add_u32_e32 v92, s56, v90
	s_waitcnt vmcnt(22)
	v_add_u32_e32 v94, s56, v92
	v_add_u32_e32 v96, s56, v94
	v_mbcnt_lo_u32_b32 v246, -1, 0
	v_mbcnt_hi_u32_b32 v246, -1, v246
	v_and_b32_e32 v247, 7, v246
	v_lshrrev_b32_e32 v248, 3, v246
	v_lshlrev_b32_e32 v247, 4, v247
	v_lshlrev_b32_e32 v249, 1, v246
	v_sub_u32_e32 v247, v247, v249
	v_mul_lo_u32 v248, v248, s56
	v_add3_u32 v244, v66, v247, v248
	v_lshl_add_u32 v245, s56, 3, v244
	v_lshl_add_u32 v246, v246, 1, s100
	s_add_i32 m0, s100, 0
	s_nop 0
	global_load_lds_dwordx4 v244, s[50:51]
	s_add_i32 m0, s100, 1024
	s_nop 0
	global_load_lds_dwordx4 v245, s[50:51]
	s_add_i32 m0, s100, 2048
	s_nop 0
	global_load_lds_dwordx4 v244, s[52:53]
	s_add_i32 m0, s100, 3072
	s_nop 0
	global_load_lds_dwordx4 v245, s[52:53]
	s_add_i32 m0, s100, 4096
	s_nop 0
	global_load_lds_dwordx4 v244, s[36:37]
	s_add_i32 m0, s100, 5120
	s_nop 0
	global_load_lds_dwordx4 v245, s[36:37]
	s_ashr_i32 s50, s55, 7
	s_lshl_b32 s1, s54, 1
	s_and_b32 s51, s1, 2
	s_lshl_b32 s1, s50, 4
	v_lshlrev_b32_e32 v32, 1, v98
	v_mov_b32_e32 v33, v64
	s_cmp_gt_u32 s50, 1
	v_lshl_add_u64 v[112:113], s[4:5], 0, v[32:33]
	v_add_u32_e32 v238, s18, v98
	v_sub_u32_e32 v239, s19, v98
	v_add_u32_e32 v239, 0x7f, v239
	v_cndmask_b32_e64 v238, v239, v238, s[48:49]
	v_lshlrev_b32_e32 v238, 11, v238
	v_lshl_add_u32 v238, v109, 1, v238
	v_mov_b32_e32 v239, 0
	v_lshl_add_u64 v[228:229], s[4:5], 0, v[238:239]
	v_mov_b32_e32 v238, 0x8000
	v_mov_b32_e32 v240, 0xffff8000
	v_cndmask_b32_e64 v238, v240, v238, s[48:49]
	v_cndmask_b32_e64 v239, -1, 0, s[48:49]
	v_lshl_add_u64 v[230:231], v[228:229], 0, v[238:239]
	v_lshl_add_u64 v[232:233], v[230:231], 0, v[238:239]
	v_lshl_add_u64 v[234:235], v[232:233], 0, v[238:239]
	v_lshlrev_b32_e32 v236, 2, v238
	v_mov_b32_e32 v237, v239
	v_mov_b32_e32 v248, 0x3fb8aa3b
	v_mov_b32_e32 v249, 0x3fb8aa3b
	v_mov_b32_e32 v238, 1.0
	v_mov_b32_e32 v239, 1.0
	v_mov_b32_e32 v247, 0x42e6d4ca
	s_cselect_b64 s[4:5], -1, 0
	s_cmp_le_i32 s51, s50
	s_movk_i32 s53, 0x110
	s_movk_i32 s52, 0x90
	v_or_b32_e32 v114, s18, v109
	s_mov_b32 s21, 0
	v_mov_b32_e32 v67, v64
	v_mov_b32_e32 v69, v64
	v_mov_b32_e32 v71, v64
	v_mov_b32_e32 v73, v64
	v_mov_b32_e32 v75, v64
	v_mov_b32_e32 v77, v64
	v_mov_b32_e32 v79, v64
	v_mov_b32_e32 v81, v64
	v_mov_b32_e32 v83, v64
	v_mov_b32_e32 v85, v64
	v_mov_b32_e32 v87, v64
	v_mov_b32_e32 v89, v64
	v_mov_b32_e32 v91, v64
	v_mov_b32_e32 v93, v64
	v_mov_b32_e32 v95, v64
	v_mov_b32_e32 v97, v64
	v_or_b32_e32 v40, s1, v109
	v_or_b32_e32 v41, s1, v98
	v_or_b32_e32 v42, s0, v98
	s_cselect_b64 s[0:1], -1, 0
	s_cmp_eq_u32 s51, 0
	s_cselect_b64 s[36:37], -1, 0
	s_and_b64 s[4:5], s[4:5], s[36:37]
	s_and_b64 s[4:5], s[4:5], exec
	s_mov_b32 s4, 0xcc00
	s_cselect_b32 s4, s4, 0x4400
	s_add_i32 s4, s4, 0
	s_lshl_b32 s5, s51, 4
	v_or_b32_e32 v43, s5, v98
	v_mov_b32_e32 v44, s4
	v_or_b32_e32 v47, 1, v40
	v_or_b32_e32 v48, 2, v40
	v_or_b32_e32 v49, 3, v40
	v_or_b32_e32 v50, s5, v107
	v_readlane_b32 s4, v255, 4
	v_mul_lo_u32 v41, v41, s53
	v_mul_lo_u32 v42, v42, s52
	v_mad_u32_u24 v45, v43, s53, v44
	v_mul_lo_u32 v46, v40, s52
	s_cmp_lt_i32 s51, s50
	v_mad_u32_u24 v44, v50, s53, v44
	v_lshl_add_u32 v51, v43, 1, s4
	v_cmp_gt_i32_e64 s[50:51], v43, v40
	v_cmp_gt_i32_e64 s[52:53], v43, v47
	v_cmp_gt_i32_e64 s[54:55], v43, v48
	v_cmp_gt_i32_e64 s[56:57], v43, v49
	v_lshl_add_u32 v43, v50, 1, s4
	s_cselect_b64 s[36:37], -1, 0
	v_cmp_gt_i32_e64 s[58:59], v50, v40
	v_cmp_gt_i32_e64 s[60:61], v50, v47
	v_cmp_gt_i32_e64 s[62:63], v50, v48
	v_cmp_gt_i32_e64 s[64:65], v50, v49
	v_add_u32_e32 v122, v45, v104
	v_add_u32_e32 v123, v51, v46
	v_add_u32_e32 v124, v44, v104
	v_add_u32_e32 v126, v43, v46
	v_add_u32_e32 v127, v155, v42
	v_add_u32_e32 v128, v156, v41
	s_waitcnt vmcnt(0)
	v_readlane_b32 s98, v250, 25
	s_nop 3
	s_lshr_b32 s98, s98, 6
	s_cmp_ge_u32 s98, 4
	s_cbranch_scc0 .Lprio_hg2
	s_setprio 1
.Lprio_hg2:
	s_branch .LBB0_270
.LBB0_269:
	v_cvt_pk_bf16_f32 v48, v24, v25
	v_cvt_pk_bf16_f32 v49, v26, v27
	v_cvt_pk_bf16_f32 v50, v16, v17
	v_cvt_pk_bf16_f32 v51, v18, v19
	v_cvt_pk_bf16_f32 v52, v8, v9
	v_cvt_pk_bf16_f32 v53, v10, v11
	v_cvt_pk_bf16_f32 v54, v4, v5
	v_cvt_pk_bf16_f32 v55, v6, v7
	v_cvt_pk_bf16_f32 v56, v28, v29
	v_cvt_pk_bf16_f32 v57, v30, v31
	v_cvt_pk_bf16_f32 v58, v20, v21
	v_cvt_pk_bf16_f32 v59, v22, v23
	v_cndmask_b32_e64 v40, v40, 0, s[58:59]
	v_bfe_u32 v44, v40, 16, 1
	v_add3_u32 v40, v40, v44, s6
	v_cvt_pk_bf16_f32 v60, v12, v13
	ds_write_b16_d16_hi v126, v40
	v_cndmask_b32_e64 v40, v41, 0, s[60:61]
	v_bfe_u32 v41, v40, 16, 1
	v_add3_u32 v40, v40, v41, s6
	v_cvt_pk_bf16_f32 v61, v14, v15
	ds_write_b16_d16_hi v126, v40 offset:144
	v_cndmask_b32_e64 v40, v42, 0, s[62:63]
	v_bfe_u32 v41, v40, 16, 1
	v_add3_u32 v40, v40, v41, s6
	v_cvt_pk_bf16_f32 v62, v0, v1
	ds_write_b16_d16_hi v126, v40 offset:288
	v_cndmask_b32_e64 v40, v43, 0, s[64:65]
	v_bfe_u32 v41, v40, 16, 1
	v_add3_u32 v40, v40, v41, s6
	v_cvt_pk_bf16_f32 v63, v2, v3
	v_add_u32_e32 v138, 0x8800, v163
	ds_write_b16_d16_hi v126, v40 offset:432
	s_waitcnt lgkmcnt(0)
	s_barrier
	ds_read_b128 v[44:47], v127
	ds_read_b128 v[40:43], v127 offset:64
	ds_read_b128 v[172:175], v162
	ds_read_b128 v[184:187], v162 offset:64
	ds_read2_b64 v[188:191], v138 offset1:4
	ds_read2_b64 v[192:195], v138 offset0:8 offset1:12
	ds_read2_b64 v[196:199], v138 offset0:16 offset1:20
	ds_read2_b64 v[200:203], v138 offset0:24 offset1:28
	s_waitcnt lgkmcnt(5)
	v_mfma_f32_16x16x32_bf16 v[172:175], v[44:47], v[172:175], 0
	s_waitcnt lgkmcnt(4)
	v_mfma_f32_16x16x32_bf16 v[172:175], v[40:43], v[184:187], v[172:175]
	s_waitcnt lgkmcnt(3)
	v_mfma_f32_16x16x32_bf16 v[172:175], v[48:51], v[188:191], v[172:175]
	s_waitcnt lgkmcnt(2)
	v_mfma_f32_16x16x32_bf16 v[172:175], v[52:55], v[192:195], v[172:175]
	s_waitcnt lgkmcnt(1)
	v_mfma_f32_16x16x32_bf16 v[172:175], v[56:59], v[196:199], v[172:175]
	s_waitcnt lgkmcnt(0)
	v_mfma_f32_16x16x32_bf16 v[172:175], v[60:63], v[200:203], v[172:175]
	s_nop 7
	v_cvt_pk_bf16_f32 v240, v172, v173
	v_cvt_pk_bf16_f32 v241, v174, v175
	global_store_dwordx2 v[228:229], v[240:241], off
	v_add_u32_e32 v182, 0x9800, v163
	ds_read_b128 v[172:175], v162 offset:2304
	ds_read_b128 v[184:187], v162 offset:2368
	ds_read2_b64 v[188:191], v182 offset0:32 offset1:36
	ds_read2_b64 v[192:195], v182 offset0:40 offset1:44
	ds_read2_b64 v[196:199], v182 offset0:48 offset1:52
	ds_read2_b64 v[200:203], v182 offset0:56 offset1:60
	s_waitcnt lgkmcnt(5)
	v_mfma_f32_16x16x32_bf16 v[172:175], v[44:47], v[172:175], 0
	s_waitcnt lgkmcnt(4)
	v_mfma_f32_16x16x32_bf16 v[172:175], v[40:43], v[184:187], v[172:175]
	s_waitcnt lgkmcnt(3)
	v_mfma_f32_16x16x32_bf16 v[172:175], v[48:51], v[188:191], v[172:175]
	s_waitcnt lgkmcnt(2)
	v_mfma_f32_16x16x32_bf16 v[172:175], v[52:55], v[192:195], v[172:175]
	s_waitcnt lgkmcnt(1)
	v_mfma_f32_16x16x32_bf16 v[172:175], v[56:59], v[196:199], v[172:175]
	s_waitcnt lgkmcnt(0)
	v_mfma_f32_16x16x32_bf16 v[172:175], v[60:63], v[200:203], v[172:175]
	s_nop 7
	v_cvt_pk_bf16_f32 v242, v172, v173
	v_cvt_pk_bf16_f32 v243, v174, v175
	global_store_dwordx2 v[230:231], v[242:243], off
	v_add_u32_e32 v182, 0xa800, v163
	ds_read_b128 v[172:175], v162 offset:4608
	ds_read_b128 v[184:187], v162 offset:4672
	ds_read2_b64 v[188:191], v182 offset0:64 offset1:68
	ds_read2_b64 v[192:195], v182 offset0:72 offset1:76
	ds_read2_b64 v[196:199], v182 offset0:80 offset1:84
	ds_read2_b64 v[200:203], v182 offset0:88 offset1:92
	s_waitcnt lgkmcnt(5)
	v_mfma_f32_16x16x32_bf16 v[172:175], v[44:47], v[172:175], 0
	s_waitcnt lgkmcnt(4)
	v_mfma_f32_16x16x32_bf16 v[172:175], v[40:43], v[184:187], v[172:175]
	s_waitcnt lgkmcnt(3)
	v_mfma_f32_16x16x32_bf16 v[172:175], v[48:51], v[188:191], v[172:175]
	s_waitcnt lgkmcnt(2)
	v_mfma_f32_16x16x32_bf16 v[172:175], v[52:55], v[192:195], v[172:175]
	s_waitcnt lgkmcnt(1)
	v_mfma_f32_16x16x32_bf16 v[172:175], v[56:59], v[196:199], v[172:175]
	s_waitcnt lgkmcnt(0)
	v_mfma_f32_16x16x32_bf16 v[172:175], v[60:63], v[200:203], v[172:175]
	s_nop 7
	v_cvt_pk_bf16_f32 v240, v172, v173
	v_cvt_pk_bf16_f32 v241, v174, v175
	global_store_dwordx2 v[232:233], v[240:241], off
	v_add_u32_e32 v182, 0xb800, v163
	ds_read_b128 v[172:175], v162 offset:6912
	ds_read_b128 v[184:187], v162 offset:6976
	ds_read2_b64 v[188:191], v182 offset0:96 offset1:100
	ds_read2_b64 v[192:195], v182 offset0:104 offset1:108
	ds_read2_b64 v[196:199], v182 offset0:112 offset1:116
	ds_read2_b64 v[200:203], v182 offset0:120 offset1:124
	s_waitcnt lgkmcnt(5)
	v_mfma_f32_16x16x32_bf16 v[172:175], v[44:47], v[172:175], 0
	s_waitcnt lgkmcnt(4)
	v_mfma_f32_16x16x32_bf16 v[172:175], v[40:43], v[184:187], v[172:175]
	s_waitcnt lgkmcnt(3)
	v_mfma_f32_16x16x32_bf16 v[48:51], v[48:51], v[188:191], v[172:175]
	s_waitcnt lgkmcnt(2)
	v_mfma_f32_16x16x32_bf16 v[48:51], v[52:55], v[192:195], v[48:51]
	s_waitcnt lgkmcnt(1)
	v_mfma_f32_16x16x32_bf16 v[48:51], v[56:59], v[196:199], v[48:51]
	s_waitcnt lgkmcnt(0)
	v_mfma_f32_16x16x32_bf16 v[48:51], v[60:63], v[200:203], v[48:51]
	s_nop 7
	v_cvt_pk_bf16_f32 v242, v48, v49
	v_cvt_pk_bf16_f32 v243, v50, v51
	global_store_dwordx2 v[234:235], v[242:243], off
	v_add_u32_e32 v138, s16, v100
	v_add_u32_e32 v139, v156, v157
	ds_read_b128 v[48:51], v138
	ds_read_b128 v[52:55], v139 offset:60928
	ds_read_b128 v[56:59], v139 offset:60992
	ds_read_b128 v[60:63], v165
	ds_read_b128 v[172:175], v139 offset:63232
	ds_read_b128 v[184:187], v139 offset:63296
	ds_read_b128 v[188:191], v166
	ds_read_b128 v[192:195], v164 offset:60928
	ds_read_b128 v[196:199], v164 offset:60992
	ds_read_b128 v[200:203], v167
	ds_read_b128 v[204:207], v164 offset:63232
	ds_read_b128 v[208:211], v164 offset:63296
	s_waitcnt lgkmcnt(11)
	v_pk_mul_f32 v[24:25], v[24:25], v[48:49]
	v_pk_mul_f32 v[26:27], v[26:27], v[50:51]
	s_waitcnt lgkmcnt(8)
	v_pk_mul_f32 v[16:17], v[16:17], v[60:61]
	v_pk_mul_f32 v[18:19], v[18:19], v[62:63]
	s_waitcnt lgkmcnt(5)
	v_pk_mul_f32 v[8:9], v[8:9], v[188:189]
	v_pk_mul_f32 v[10:11], v[10:11], v[190:191]
	s_waitcnt lgkmcnt(2)
	v_pk_mul_f32 v[4:5], v[4:5], v[200:201]
	v_pk_mul_f32 v[6:7], v[6:7], v[202:203]
	v_mfma_f32_16x16x32_bf16 v[24:27], v[52:55], v[44:47], v[24:27]
	v_mfma_f32_16x16x32_bf16 v[16:19], v[172:175], v[44:47], v[16:19]
	v_mfma_f32_16x16x32_bf16 v[8:11], v[192:195], v[44:47], v[8:11]
	s_waitcnt lgkmcnt(1)
	v_mfma_f32_16x16x32_bf16 v[4:7], v[204:207], v[44:47], v[4:7]
	v_mfma_f32_16x16x32_bf16 v[24:27], v[56:59], v[40:43], v[24:27]
	v_mfma_f32_16x16x32_bf16 v[16:19], v[184:187], v[40:43], v[16:19]
	v_mfma_f32_16x16x32_bf16 v[8:11], v[196:199], v[40:43], v[8:11]
	s_waitcnt lgkmcnt(0)
	v_mfma_f32_16x16x32_bf16 v[4:7], v[208:211], v[40:43], v[4:7]
	ds_read_b128 v[48:51], v158 offset:9216
	ds_read_b128 v[52:55], v158 offset:9280
	ds_read_b128 v[56:59], v138 offset:256
	ds_read_b128 v[60:63], v138 offset:320
	ds_read_b128 v[172:175], v158 offset:11520
	ds_read_b128 v[184:187], v158 offset:11584
	ds_read_b128 v[188:191], v158 offset:13824
	ds_read_b128 v[192:195], v158 offset:13888
	ds_read_b128 v[196:199], v138 offset:384
	ds_read_b128 v[200:203], v138 offset:448
	ds_read_b128 v[204:207], v158 offset:16128
	ds_read_b128 v[208:211], v158 offset:16192
	s_waitcnt lgkmcnt(9)
	v_pk_mul_f32 v[28:29], v[28:29], v[56:57]
	v_pk_mul_f32 v[30:31], v[30:31], v[58:59]
	s_waitcnt lgkmcnt(8)
	v_pk_mul_f32 v[20:21], v[20:21], v[60:61]
	v_pk_mul_f32 v[22:23], v[22:23], v[62:63]
	s_waitcnt lgkmcnt(3)
	v_pk_mul_f32 v[12:13], v[12:13], v[196:197]
	v_pk_mul_f32 v[14:15], v[14:15], v[198:199]
	s_waitcnt lgkmcnt(2)
	v_pk_mul_f32 v[0:1], v[0:1], v[200:201]
	v_pk_mul_f32 v[2:3], v[2:3], v[202:203]
	v_mfma_f32_16x16x32_bf16 v[28:31], v[48:51], v[44:47], v[28:31]
	v_mfma_f32_16x16x32_bf16 v[20:23], v[172:175], v[44:47], v[20:23]
	v_mfma_f32_16x16x32_bf16 v[12:15], v[188:191], v[44:47], v[12:15]
	s_waitcnt lgkmcnt(1)
	v_mfma_f32_16x16x32_bf16 v[0:3], v[204:207], v[44:47], v[0:3]
	v_mfma_f32_16x16x32_bf16 v[28:31], v[52:55], v[40:43], v[28:31]
	v_mfma_f32_16x16x32_bf16 v[20:23], v[184:187], v[40:43], v[20:23]
	v_mfma_f32_16x16x32_bf16 v[12:15], v[192:195], v[40:43], v[12:15]
	s_waitcnt lgkmcnt(0)
	v_mfma_f32_16x16x32_bf16 v[0:3], v[208:211], v[40:43], v[0:3]
	v_lshl_add_u64 v[228:229], v[228:229], 0, v[236:237]
	v_lshl_add_u64 v[230:231], v[230:231], 0, v[236:237]
	v_lshl_add_u64 v[232:233], v[232:233], 0, v[236:237]
	v_lshl_add_u64 v[234:235], v[234:235], 0, v[236:237]
	s_add_i32 s21, s21, 64
	s_sub_i32 s19, s19, 64
	s_cmpk_lg_i32 s21, 0x400
	s_barrier
	s_cbranch_scc0 .LBB0_260

.LBB0_538:
	s_or_b64 exec, exec, s[0:1]
	v_and_b32_e32 v51, 64, v178
	v_xor_b32_e32 v50, 16, v178
	v_add_u32_e32 v51, 64, v51
	v_cmp_lt_i32_e32 vcc, v50, v51
	s_ashr_i32 s0, s2, 2
	v_bfe_u32 v46, v44, 4, 2
	v_cndmask_b32_e32 v50, v178, v50, vcc
	s_and_b32 s2, s0, -16
	v_lshlrev_b32_e32 v122, 2, v50
	v_xor_b32_e32 v50, 32, v178
	v_or_b32_e32 v120, s2, v45
	v_lshlrev_b32_e32 v44, 4, v44
	v_or_b32_e32 v121, v48, v45
	v_lshlrev_b32_e32 v106, 2, v46
	v_cmp_lt_i32_e32 vcc, v50, v51
	v_lshrrev_b32_e32 v45, 2, v45
	v_and_b32_e32 v44, 0xf0, v44
	v_readlane_b32 s1, v255, 5
	v_cndmask_b32_e32 v50, v178, v50, vcc
	v_or3_b32 v45, v106, v45, s2
	s_movk_i32 s0, 0x110
	s_movk_i32 s4, 0x120
	v_add_u32_e32 v47, 0, v44
	v_add_u32_e32 v44, s1, v44
	v_lshl_add_u32 v48, v46, 4, 0
	v_lshlrev_b32_e32 v123, 2, v50
	v_and_b32_e32 v49, 24, v49
	v_cmp_eq_u32_e64 s[38:39], 0, v46
	v_mul_lo_u32 v46, v107, s0
	v_mul_lo_u32 v50, v107, s4
	v_mul_lo_u32 v51, v113, s0
	v_mul_lo_u32 v52, v113, s4
	v_mul_lo_u32 v53, v114, s0
	v_mul_lo_u32 v54, v114, s4
	v_mul_lo_u32 v55, v115, s0
	v_mul_lo_u32 v56, v115, s4
	v_mul_lo_u32 v57, v116, s0
	v_mul_lo_u32 v58, v116, s4
	v_mul_lo_u32 v59, v117, s0
	v_mul_lo_u32 v65, v117, s4
	v_mul_lo_u32 v98, v118, s0
	v_mul_lo_u32 v99, v118, s4
	v_mul_lo_u32 v100, v119, s0
	v_mul_lo_u32 v101, v119, s4
	v_mul_lo_u32 v103, v120, s0
	v_mul_lo_u32 v45, v45, s4
	v_add3_u32 v124, s1, v49, v45
	v_add_u32_e32 v132, v47, v46
	v_add_u32_e32 v133, v44, v50
	v_add_u32_e32 v134, v47, v51
	v_add_u32_e32 v135, v44, v52
	v_add_u32_e32 v136, v47, v53
	v_add_u32_e32 v137, v44, v54
	v_add_u32_e32 v142, v47, v55
	v_add_u32_e32 v143, v44, v56
	v_add_u32_e32 v144, v47, v57
	v_add_u32_e32 v145, v44, v58
	v_add_u32_e32 v146, v47, v59
	v_add_u32_e32 v147, v44, v65
	v_add_u32_e32 v148, v47, v98
	v_add_u32_e32 v149, v44, v99
	v_add_u32_e32 v150, v47, v100
	v_add_u32_e32 v151, v44, v101
	v_add_u32_e32 v152, v48, v103
	s_waitcnt vmcnt(0)
	v_mov_b64_e32 v[48:49], v[94:95]
	v_mov_b64_e32 v[44:45], v[90:91]
	v_mov_b64_e32 v[52:53], v[86:87]
	v_mov_b64_e32 v[56:57], v[82:83]
	s_sub_i32 s3, s2, 64
	v_or_b32_e32 v125, 16, v106
	v_or_b32_e32 v126, 32, v106
	v_or_b32_e32 v127, 48, v106
	v_or_b32_e32 v128, 0x50, v106
	v_or_b32_e32 v129, 0x60, v106
	v_or_b32_e32 v130, 0x70, v106
	v_or_b32_e32 v131, 0x80, v106
	v_readlane_b32 s4, v254, 25
	v_readlane_b32 s19, v254, 24
	v_mov_b64_e32 v[50:51], v[96:97]
	v_mov_b64_e32 v[46:47], v[92:93]
	v_mov_b64_e32 v[54:55], v[88:89]
	v_mov_b64_e32 v[58:59], v[84:85]
	v_readlane_b32 s98, v250, 25
	s_nop 3
	s_lshr_b32 s98, s98, 6
	s_cmp_ge_u32 s98, 4
	s_cbranch_scc0 .Lprio_da
	s_setprio 1
.Lprio_da:
	s_branch .LBB0_540
.LBB0_539:
	s_or_b64 exec, exec, s[0:1]
	v_readlane_b32 s0, v254, 26
	s_waitcnt vmcnt(9)
	v_mov_b64_e32 v[84:85], v[58:59]
	v_mov_b64_e32 v[88:89], v[54:55]
	v_mov_b64_e32 v[92:93], v[46:47]
	s_waitcnt vmcnt(8)
	v_mov_b64_e32 v[96:97], v[50:51]
	s_add_i32 s4, s4, s0
	s_and_b64 vcc, exec, s[8:9]
	v_mov_b64_e32 v[82:83], v[56:57]
	v_mov_b64_e32 v[86:87], v[52:53]
	v_mov_b64_e32 v[90:91], v[44:45]
	v_mov_b64_e32 v[94:95], v[48:49]
	s_mov_b32 s19, s5
	s_barrier
	s_cbranch_vccnz .LBB0_560

.LBB0_560:
	s_setprio 0
	s_mov_b64 s[0:1], 0
